# phase 0: conv-1 bias partial sums keep 8 k-steps of loads in flight per wait (was one load pair per wait)
# speedup vs baseline: 1.0549x; 1.0031x over previous
.LBB0_723:
	s_or_b64 exec, exec, s[2:3]
	v_readlane_b32 s2, v246, 27
	v_readlane_b32 s3, v246, 28
	s_and_b64 vcc, exec, s[2:3]
	v_readlane_b32 s4, v244, 34
	s_cbranch_vccz .LBB0_727
	s_nop 0
	v_mov_b32_e32 v0, s4
	s_waitcnt vmcnt(0)
	ds_read2_b64 v[10:13], v0 offset0:13 offset1:14
	v_readlane_b32 s2, v246, 29
	v_and_b32_e32 v6, 0x7f, v150
	s_nop 0
	v_add_u32_e32 v1, s2, v150
	v_and_b32_e32 v0, 0xffffff80, v1
	v_readlane_b32 s2, v246, 32
	v_or_b32_e32 v7, 0x7f, v1
	v_readlane_b32 s3, v246, 33
	v_ashrrev_i32_e32 v1, 31, v0
	v_lshlrev_b64 v[4:5], 9, v[0:1]
	s_waitcnt lgkmcnt(0)
	v_lshl_add_u64 v[2:3], v[12:13], 0, s[2:3]
	v_readlane_b32 s2, v246, 30
	v_lshl_or_b32 v4, v6, 2, v4
	v_readlane_b32 s3, v246, 31
	v_lshl_add_u64 v[2:3], v[2:3], 0, v[4:5]
	v_add_u32_e32 v8, -1, v0
	v_lshl_add_u64 v[4:5], v[10:11], 0, s[2:3]
	v_lshl_add_u64 v[4:5], v[0:1], 2, v[4:5]
	v_mov_b32_e32 v1, 0
	s_mov_b64 s[2:3], 0
	s_movk_i32 s4, 16
.Lp0c1_loop:
	global_load_dword v12, v[4:5], off
	global_load_dword v13, v[4:5], off offset:4
	global_load_dword v14, v[4:5], off offset:8
	global_load_dword v15, v[4:5], off offset:12
	global_load_dword v16, v[4:5], off offset:16
	global_load_dword v17, v[4:5], off offset:20
	global_load_dword v18, v[4:5], off offset:24
	global_load_dword v19, v[4:5], off offset:28
	global_load_dword v20, v[2:3], off
	global_load_dword v21, v[2:3], off offset:512
	global_load_dword v22, v[2:3], off offset:1024
	global_load_dword v23, v[2:3], off offset:1536
	global_load_dword v24, v[2:3], off offset:2048
	global_load_dword v25, v[2:3], off offset:2560
	global_load_dword v26, v[2:3], off offset:3072
	global_load_dword v27, v[2:3], off offset:3584
	v_lshl_add_u64 v[4:5], v[4:5], 0, 32
	v_add_co_u32_e32 v2, vcc, 0x1000, v2
	s_nop 1
	v_addc_co_u32_e32 v3, vcc, 0, v3, vcc
	s_waitcnt vmcnt(0)
	v_fmac_f32_e32 v1, v12, v20
	v_fmac_f32_e32 v1, v13, v21
	v_fmac_f32_e32 v1, v14, v22
	v_fmac_f32_e32 v1, v15, v23
	v_fmac_f32_e32 v1, v16, v24
	v_fmac_f32_e32 v1, v17, v25
	v_fmac_f32_e32 v1, v18, v26
	v_fmac_f32_e32 v1, v19, v27
	s_add_i32 s4, s4, -1
	s_cmp_lg_u32 s4, 0
	s_cbranch_scc1 .Lp0c1_loop
	s_or_b64 exec, exec, s[2:3]
	v_readlane_b32 s4, v244, 34
	v_readlane_b32 s2, v246, 34
	s_nop 0
	v_mov_b32_e32 v2, s4
	ds_read_b64 v[2:3], v2 offset:120
	v_add_u32_e32 v0, s2, v0
	v_or_b32_e32 v4, v0, v6
	v_ashrrev_i32_e32 v5, 31, v4
	s_waitcnt lgkmcnt(0)
	v_lshl_add_u64 v[2:3], v[4:5], 2, v[2:3]
	flat_store_dword v[2:3], v1
